# v28 + converted bf16 weight stores sc1 nt (streaming write-through)
# baseline (speedup 1.0000x reference)
; #define LAS __attribute__((address_space(3)))
; __device__ __forceinline__ unsigned cvt_pk_bf16(float lo, float hi) { unsigned r; asm volatile("v_cvt_pk_bf16_f32 %0, %1, %2" : "=v"(r) : "v"(lo), "v"(hi)); return r; }
; __device__ __forceinline__ void tr_item32(const float* W, int K, int N, bf16_t* WT, const float* gsc, bool swz, LAS float* scr, int item, int lane) {
;     ...
;     const int c = lane & 3;
; #pragma unroll
;     for (int hf = 0; hf < 2; ++hf) {
; #pragma unroll
;         for (int i = 0; i < 4; ++i)
; #pragma unroll
;             for (int e = 0; e < 4; ++e) scr[(kr + 8 * i) * 33 + 4 * n4 + e] = v[hf][i][e];
;         asm volatile("s_waitcnt lgkmcnt(0)" ::: "memory");
; #pragma unroll
;         for (int j = 0; j < 2; ++j) { const int n = (lane >> 2) + 16 * j; const LAS float* sp = scr + (8 * c) * 33 + n;
;             u32x4 o; o.x = cvt_pk_bf16(sp[0 * 33], sp[1 * 33]); o.y = cvt_pk_bf16(sp[2 * 33], sp[3 * 33]); o.z = cvt_pk_bf16(sp[4 * 33], sp[5 * 33]); o.w = cvt_pk_bf16(sp[6 * 33], sp[7 * 33]);
;             *(u32x4*)(WT + (size_t)(rbase + 32 * hf + n) * K + k0 + 8 * c) = o; }
;         asm volatile("s_waitcnt lgkmcnt(0)" ::: "memory");
;     }
; __device__ __forceinline__ void convert_layer(const Args& a, int l, bf16_t* slot, LAS float* scr, int gw, int NGW, int lane) {
;     for (int it = gw; it < J_LAYER; it += NGW) convert_item(a, l, slot, scr, it, lane);
; }
.LBB0_26:
	s_waitcnt vmcnt(7)
	ds_write2_b32 v43, v28, v29 offset1:1
	ds_write2_b32 v43, v30, v31 offset0:2 offset1:3
	v_add_u32_e32 v29, 0x428, v43
	v_add_u32_e32 v28, 0x420, v43
	s_waitcnt vmcnt(5)
	ds_write2_b32 v29, v26, v27 offset1:1
	v_add_u32_e32 v26, 0x840, v43
	v_add_u32_e32 v27, 0x848, v43
	v_add_u32_e32 v30, 0xc60, v43
	v_add_u32_e32 v31, 0xc68, v43
	ds_write2_b32 v28, v24, v25 offset1:1
	s_waitcnt vmcnt(3)
	ds_write2_b32 v26, v20, v21 offset1:1
	ds_write2_b32 v27, v22, v23 offset1:1
	s_waitcnt vmcnt(1)
	ds_write2_b32 v30, v16, v17 offset1:1
	ds_write2_b32 v31, v18, v19 offset1:1
	s_waitcnt lgkmcnt(0)
	ds_read2_b32 v[16:17], v41 offset1:33
	s_waitcnt lgkmcnt(0)
	v_cvt_pk_bf16_f32 v16, v16, v17
	ds_read2_b32 v[18:19], v41 offset0:66 offset1:99
	s_ashr_i32 s35, s34, 31
	s_waitcnt lgkmcnt(0)
	v_cvt_pk_bf16_f32 v17, v18, v19
	ds_read2_b32 v[18:19], v41 offset0:132 offset1:165
	s_lshl_b64 s[28:29], s[34:35], 1
	s_waitcnt lgkmcnt(0)
	v_cvt_pk_bf16_f32 v18, v18, v19
	ds_read2_b32 v[20:21], v41 offset0:198 offset1:231
	s_add_u32 s26, s26, s28
	v_add_u32_e32 v24, s33, v40
	s_addc_u32 s27, s27, s29
	s_waitcnt lgkmcnt(0)
	v_cvt_pk_bf16_f32 v19, v20, v21
	v_ashrrev_i32_e32 v20, 31, v24
	v_lshl_add_u64 v[22:23], s[26:27], 0, v[32:33]
	v_mul_lo_u32 v36, s24, v20
	v_mul_lo_u32 v37, s25, v24
	v_mad_u64_u32 v[24:25], s[26:27], s24, v24, 0
	v_add3_u32 v25, v25, v36, v37
	v_lshl_add_u64 v[24:25], v[24:25], 1, v[22:23]
	ds_read2_b32 v[20:21], v41 offset0:16 offset1:49
	global_store_dwordx4 v[24:25], v[16:19], off sc1 nt
	s_add_i32 s28, s33, 32
	s_add_i32 s7, s7, s44
	s_waitcnt lgkmcnt(0)
	v_cvt_pk_bf16_f32 v16, v20, v21
	ds_read2_b32 v[18:19], v41 offset0:82 offset1:115
	s_waitcnt lgkmcnt(0)
	v_cvt_pk_bf16_f32 v17, v18, v19
	ds_read2_b32 v[18:19], v41 offset0:148 offset1:181
	s_waitcnt lgkmcnt(0)
	v_cvt_pk_bf16_f32 v18, v18, v19
	ds_read2_b32 v[20:21], v41 offset0:214 offset1:247
	s_waitcnt lgkmcnt(0)
	v_cvt_pk_bf16_f32 v19, v20, v21
	v_add_u32_e32 v20, s33, v42
	v_ashrrev_i32_e32 v21, 31, v20
	v_mul_lo_u32 v24, s24, v21
	v_mul_lo_u32 v25, s25, v20
	v_mad_u64_u32 v[20:21], s[26:27], s24, v20, 0
	v_add3_u32 v21, v21, v24, v25
	v_lshl_add_u64 v[20:21], v[20:21], 1, v[22:23]
	global_store_dwordx4 v[20:21], v[16:19], off sc1 nt
	s_waitcnt lgkmcnt(0)
	ds_write2_b32 v43, v12, v13 offset1:1
	ds_write2_b32 v43, v14, v15 offset0:2 offset1:3
	ds_write2_b32 v28, v8, v9 offset1:1
	ds_write2_b32 v29, v10, v11 offset1:1
	ds_write2_b32 v26, v4, v5 offset1:1
	ds_write2_b32 v27, v6, v7 offset1:1
	s_waitcnt vmcnt(2)
	ds_write2_b32 v30, v0, v1 offset1:1
	ds_write2_b32 v31, v2, v3 offset1:1
	s_waitcnt lgkmcnt(0)
	ds_read2_b32 v[0:1], v41 offset1:33
	s_waitcnt lgkmcnt(0)
	v_cvt_pk_bf16_f32 v0, v0, v1
	ds_read2_b32 v[2:3], v41 offset0:66 offset1:99
	s_waitcnt lgkmcnt(0)
	v_cvt_pk_bf16_f32 v1, v2, v3
	ds_read2_b32 v[2:3], v41 offset0:132 offset1:165
	s_waitcnt lgkmcnt(0)
	v_cvt_pk_bf16_f32 v2, v2, v3
	ds_read2_b32 v[4:5], v41 offset0:198 offset1:231
	v_add_u32_e32 v6, s28, v40
	s_waitcnt lgkmcnt(0)
	v_cvt_pk_bf16_f32 v3, v4, v5
	v_ashrrev_i32_e32 v4, 31, v6
	v_mul_lo_u32 v8, s24, v4
	v_mul_lo_u32 v9, s25, v6
	v_mad_u64_u32 v[6:7], s[26:27], s24, v6, 0
	v_add3_u32 v7, v7, v8, v9
	v_lshl_add_u64 v[6:7], v[6:7], 1, v[22:23]
	ds_read2_b32 v[4:5], v41 offset0:16 offset1:49
	global_store_dwordx4 v[6:7], v[0:3], off sc1 nt
	s_cmpk_lt_i32 s7, 0x3140
	s_waitcnt lgkmcnt(0)
	v_cvt_pk_bf16_f32 v0, v4, v5
	ds_read2_b32 v[2:3], v41 offset0:82 offset1:115
	s_waitcnt lgkmcnt(0)
	v_cvt_pk_bf16_f32 v1, v2, v3
	ds_read2_b32 v[2:3], v41 offset0:148 offset1:181
	s_waitcnt lgkmcnt(0)
	v_cvt_pk_bf16_f32 v2, v2, v3
	ds_read2_b32 v[4:5], v41 offset0:214 offset1:247
	s_waitcnt lgkmcnt(0)
	v_cvt_pk_bf16_f32 v3, v4, v5
	v_add_u32_e32 v4, s28, v42
	v_ashrrev_i32_e32 v5, 31, v4
	v_mul_lo_u32 v6, s24, v5
	v_mul_lo_u32 v7, s25, v4
	v_mad_u64_u32 v[4:5], s[24:25], s24, v4, 0
	v_add3_u32 v5, v5, v6, v7
	v_lshl_add_u64 v[4:5], v[4:5], 1, v[22:23]
	global_store_dwordx4 v[4:5], v[0:3], off sc1 nt
	s_waitcnt lgkmcnt(0)
	s_cbranch_scc0 .LBB0_71

; #define LAS __attribute__((address_space(3)))
; __device__ __forceinline__ unsigned cvt_pk_bf16(float lo, float hi) { unsigned r; asm volatile("v_cvt_pk_bf16_f32 %0, %1, %2" : "=v"(r) : "v"(lo), "v"(hi)); return r; }
; __device__ __forceinline__ void tr_item32(const float* W, int K, int N, bf16_t* WT, const float* gsc, bool swz, LAS float* scr, int item, int lane) {
;     ...
;     const int c = lane & 3;
; #pragma unroll
;     for (int hf = 0; hf < 2; ++hf) {
; #pragma unroll
;         for (int i = 0; i < 4; ++i)
; #pragma unroll
;             for (int e = 0; e < 4; ++e) scr[(kr + 8 * i) * 33 + 4 * n4 + e] = v[hf][i][e];
;         asm volatile("s_waitcnt lgkmcnt(0)" ::: "memory");
; #pragma unroll
;         for (int j = 0; j < 2; ++j) { const int n = (lane >> 2) + 16 * j; const LAS float* sp = scr + (8 * c) * 33 + n;
;             u32x4 o; o.x = cvt_pk_bf16(sp[0 * 33], sp[1 * 33]); o.y = cvt_pk_bf16(sp[2 * 33], sp[3 * 33]); o.z = cvt_pk_bf16(sp[4 * 33], sp[5 * 33]); o.w = cvt_pk_bf16(sp[6 * 33], sp[7 * 33]);
;             *(u32x4*)(WT + (size_t)(rbase + 32 * hf + n) * K + k0 + 8 * c) = o; }
;         asm volatile("s_waitcnt lgkmcnt(0)" ::: "memory");
;     }
; __device__ __forceinline__ void convert_dynamic(const Args& a, int l, bf16_t* slot, LAS float* scr, unsigned* counter, int lane) {
;     for (;;) {
;         unsigned it = 0u; if (lane == 0) it = __hip_atomic_fetch_add(counter, 4u, __ATOMIC_RELAXED, __HIP_MEMORY_SCOPE_AGENT);
;         it = (unsigned)__builtin_amdgcn_readfirstlane((int)it);
;         if (it >= (unsigned)J_LAYER) break;
;         for (unsigned u = 0; u < 4u && it + u < (unsigned)J_LAYER; ++u) convert_item(a, l, slot, scr, (int)(it + u), lane);
;     }
.LBB0_697:
	s_waitcnt vmcnt(7)
	ds_write2_b32 v251, v38, v39 offset1:1
	ds_write2_b32 v251, v40, v41 offset0:2 offset1:3
	v_add_u32_e32 v39, 0x428, v251
	v_add_u32_e32 v38, 0x420, v251
	s_waitcnt vmcnt(5)
	ds_write2_b32 v39, v36, v37 offset1:1
	v_add_u32_e32 v36, 0x840, v251
	v_add_u32_e32 v37, 0x848, v251
	v_add_u32_e32 v40, 0xc60, v251
	v_add_u32_e32 v41, 0xc68, v251
	ds_write2_b32 v38, v34, v35 offset1:1
	s_waitcnt vmcnt(3)
	ds_write2_b32 v36, v30, v31 offset1:1
	ds_write2_b32 v37, v32, v33 offset1:1
	s_waitcnt vmcnt(1)
	ds_write2_b32 v40, v26, v27 offset1:1
	ds_write2_b32 v41, v28, v29 offset1:1
	s_waitcnt lgkmcnt(0)
	ds_read2_b32 v[26:27], v226 offset1:33
	s_waitcnt lgkmcnt(0)
	v_cvt_pk_bf16_f32 v26, v26, v27
	ds_read2_b32 v[28:29], v226 offset0:66 offset1:99
	s_waitcnt lgkmcnt(0)
	v_cvt_pk_bf16_f32 v27, v28, v29
	ds_read2_b32 v[28:29], v226 offset0:132 offset1:165
	s_lshl_b32 s2, s23, 1
	s_waitcnt lgkmcnt(0)
	v_cvt_pk_bf16_f32 v28, v28, v29
	ds_read2_b32 v[30:31], v226 offset0:198 offset1:231
	s_add_u32 s10, s10, s2
	v_add_u32_e32 v34, s21, v237
	s_addc_u32 s11, s11, 0
	v_mov_b32_e32 v151, v1
	s_waitcnt lgkmcnt(0)
	v_cvt_pk_bf16_f32 v29, v30, v31
	v_ashrrev_i32_e32 v30, 31, v34
	v_lshl_add_u64 v[32:33], s[10:11], 0, v[150:151]
	v_mul_lo_u32 v42, s8, v30
	v_mul_lo_u32 v43, s9, v34
	v_mad_u64_u32 v[34:35], s[10:11], s8, v34, 0
	v_add3_u32 v35, v35, v42, v43
	v_lshl_add_u64 v[34:35], v[34:35], 1, v[32:33]
	ds_read2_b32 v[30:31], v226 offset0:16 offset1:49
	global_store_dwordx4 v[34:35], v[26:29], off sc1 nt
	s_add_i32 s2, s21, 32
	s_waitcnt lgkmcnt(0)
	v_cvt_pk_bf16_f32 v26, v30, v31
	ds_read2_b32 v[28:29], v226 offset0:82 offset1:115
	s_waitcnt lgkmcnt(0)
	v_cvt_pk_bf16_f32 v27, v28, v29
	ds_read2_b32 v[28:29], v226 offset0:148 offset1:181
	s_waitcnt lgkmcnt(0)
	v_cvt_pk_bf16_f32 v28, v28, v29
	ds_read2_b32 v[30:31], v226 offset0:214 offset1:247
	s_waitcnt lgkmcnt(0)
	v_cvt_pk_bf16_f32 v29, v30, v31
	v_add_u32_e32 v30, s21, v245
	v_ashrrev_i32_e32 v31, 31, v30
	v_mul_lo_u32 v34, s8, v31
	v_mul_lo_u32 v35, s9, v30
	v_mad_u64_u32 v[30:31], s[10:11], s8, v30, 0
	v_add3_u32 v31, v31, v34, v35
	v_lshl_add_u64 v[30:31], v[30:31], 1, v[32:33]
	global_store_dwordx4 v[30:31], v[26:29], off sc1 nt
	s_waitcnt lgkmcnt(0)
	ds_write2_b32 v251, v22, v23 offset1:1
	ds_write2_b32 v251, v24, v25 offset0:2 offset1:3
	ds_write2_b32 v38, v18, v19 offset1:1
	ds_write2_b32 v39, v20, v21 offset1:1
	ds_write2_b32 v36, v14, v15 offset1:1
	ds_write2_b32 v37, v16, v17 offset1:1
	s_waitcnt vmcnt(2)
	ds_write2_b32 v40, v10, v11 offset1:1
	ds_write2_b32 v41, v12, v13 offset1:1
	s_waitcnt lgkmcnt(0)
	ds_read2_b32 v[10:11], v226 offset1:33
	s_waitcnt lgkmcnt(0)
	v_cvt_pk_bf16_f32 v10, v10, v11
	ds_read2_b32 v[12:13], v226 offset0:66 offset1:99
	s_waitcnt lgkmcnt(0)
	v_cvt_pk_bf16_f32 v11, v12, v13
	ds_read2_b32 v[12:13], v226 offset0:132 offset1:165
	s_waitcnt lgkmcnt(0)
	v_cvt_pk_bf16_f32 v12, v12, v13
	ds_read2_b32 v[14:15], v226 offset0:198 offset1:231
	v_add_u32_e32 v16, s2, v237
	s_waitcnt lgkmcnt(0)
	v_cvt_pk_bf16_f32 v13, v14, v15
	v_ashrrev_i32_e32 v14, 31, v16
	v_mul_lo_u32 v18, s8, v14
	v_mul_lo_u32 v19, s9, v16
	v_mad_u64_u32 v[16:17], s[10:11], s8, v16, 0
	v_add3_u32 v17, v17, v18, v19
	v_lshl_add_u64 v[16:17], v[16:17], 1, v[32:33]
	ds_read2_b32 v[14:15], v226 offset0:16 offset1:49
	global_store_dwordx4 v[16:17], v[10:13], off sc1 nt
	s_waitcnt lgkmcnt(0)
	s_nop 0
	v_cvt_pk_bf16_f32 v10, v14, v15
	ds_read2_b32 v[12:13], v226 offset0:82 offset1:115
	s_waitcnt lgkmcnt(0)
	v_cvt_pk_bf16_f32 v11, v12, v13
	ds_read2_b32 v[12:13], v226 offset0:148 offset1:181
	s_waitcnt lgkmcnt(0)
	v_cvt_pk_bf16_f32 v12, v12, v13
	ds_read2_b32 v[14:15], v226 offset0:214 offset1:247
	s_waitcnt lgkmcnt(0)
	v_cvt_pk_bf16_f32 v13, v14, v15
	v_add_u32_e32 v14, s2, v245
	v_ashrrev_i32_e32 v15, 31, v14
	v_mul_lo_u32 v16, s8, v15
	v_mul_lo_u32 v17, s9, v14
	v_mad_u64_u32 v[14:15], s[8:9], s8, v14, 0
	s_add_i32 s2, s55, 1
	v_add3_u32 v15, v15, v16, v17
	s_cmp_lt_u32 s55, 3
	v_lshl_add_u64 v[14:15], v[14:15], 1, v[32:33]
	s_cselect_b64 s[8:9], -1, 0
	s_add_i32 s20, s20, 1
	global_store_dwordx4 v[14:15], v[10:13], off sc1 nt
	s_cmpk_lt_u32 s20, 0x3140
	s_waitcnt lgkmcnt(0)
	s_cselect_b64 s[10:11], -1, 0
	s_and_b64 s[8:9], s[8:9], s[10:11]
	s_andn2_b64 vcc, exec, s[8:9]
	s_mov_b32 s55, s2
	s_cbranch_vccnz .LBB0_689
